# GEMM K-loop: the two k=1 B1-fragment LDS reads of sections 2 and 6 issued inside the following MFMA block
# baseline (speedup 1.0000x reference)
; #define LDA(dst, b, h) for (int m = 0; m < 4; ++m) for (int k = 0; k < 2; ++k) \
;     dst[m][k] = *reinterpret_cast<const bf16x8*>(SA(b, h) + lds_byte(wr * 64 + m * 16 + fr, k * 32 + fq * 8))
; #define LDB(dst, b, h) for (int n = 0; n < 2; ++n) for (int k = 0; k < 2; ++k) \
;     dst[n][k] = *reinterpret_cast<const bf16x8*>(SB(b, h) + lds_byte(wc * 32 + n * 16 + fr, k * 32 + fq * 8))
; #define MMA(ai, bj, At_, Bt_) do { __builtin_amdgcn_s_setprio(1); \
;     for (int m = 0; m < 4; ++m) for (int n = 0; n < 2; ++n) for (int k = 0; k < 2; ++k) \
;       acc[ai][bj][m][n] = __builtin_amdgcn_mfma_f32_16x16x32_bf16(Bt_[n][k], At_[m][k], acc[ai][bj][m][n], 0, 0, 0); \
;     __builtin_amdgcn_s_setprio(0); } while (0)
; #define WAIT_V(n) asm volatile("s_waitcnt vmcnt(" #n ")" ::: "memory")
; #define WAIT_L(n) asm volatile("s_waitcnt lgkmcnt(" #n ")" ::: "memory")
; #define BAR __builtin_amdgcn_s_barrier()
; #define SCHED __builtin_amdgcn_sched_barrier(0)
; #define STG(P, PTR, LD, O0) do { const bf16_t* _g = (PTR); \
;     __builtin_amdgcn_global_load_lds((const unsigned*)(_g + O0), (lds_u32*)((P) + swave * 1024), 16, 0, 0); \
;     __builtin_amdgcn_global_load_lds((const unsigned*)(_g + (size_t)64 * (LD) + O0), (lds_u32*)((P) + swave * 1024 + 8192), 16, 0, 0); } while (0)
; #define LDA(dst, b, h) for (int m = 0; m < 4; ++m) for (int k = 0; k < 2; ++k) \
;     dst[m][k] = *reinterpret_cast<const bf16x8*>(SA(b, h) + lds_byte(wr * 64 + m * 16 + fr, k * 32 + fq * 8))
; #define WAIT_V(n) asm volatile("s_waitcnt vmcnt(" #n ")" ::: "memory")
; __device__ __forceinline__ void gemm_stream(int swave, const GemmJob& J, char* shm, int vb, int G) {
;     ...
;     for (int t = 0; t < nt; t += 2) {
;       const bool last = (t == nt - 2);
;       const bf16_t* xA = last ? nA : cA; const bf16_t* xA1 = last ? nA1 : cA1; const int k2 = last ? 0 : t + 2;
;       const bf16_t* b2 = last ? nB : cB + (size_t)(t + 2) * 64; const bf16_t* b3 = b2 + 64;
;       LDB(B0, 0, 0); SCHED; LDA(At, 0, 0); STGA(SA(1, 1), cA, cA1, t + 1, 1);
;       WAIT_L(8); BAR; WAIT_L(0); MMA(0, 0, At, B0); BAR; SCHED;
;       LDB(B1, 0, 1); STG(SB(0, 0), b2, ldb, offB0);
;       BAR; WAIT_L(0); MMA(0, 1, At, B1); BAR;
;       LDA(At, 0, 1); STGA(SA(0, 0), xA, xA1, k2, 0);
;       BAR; WAIT_L(0); MMA(1, 0, At, B0); BAR; SCHED;
;       STG(SB(0, 1), b2 + hB, ldb, offB0);
;       WAIT_V(6); BAR; MMA(1, 1, At, B1); BAR;
.LBB0_729:
	ds_read_b128 v[164:167], v139
	ds_read_b128 v[168:171], v139 offset:1024
	ds_read_b128 v[172:175], v139 offset:2048
	ds_read_b128 v[176:179], v139 offset:3072
	s_cmp_eq_u32 s49, s29
	s_cselect_b64 s[68:69], -1, 0
	s_and_b64 s[64:65], s[68:69], exec
	s_cselect_b32 s52, s10, s8
	s_cselect_b32 s64, s11, s9
	s_add_i32 s33, s2, 2
	s_and_b64 s[68:69], s[68:69], exec
	s_cselect_b32 s71, s15, s21
	s_cselect_b32 s70, s14, s20
	s_cselect_b32 s68, 0, s33
	s_cselect_b32 s65, s12, s16
	s_cselect_b32 s66, s13, s17
	s_or_b32 s2, s2, 1
	s_cmp_lt_u32 s2, s36
	s_cselect_b64 vcc, -1, 0
	s_and_b64 s[2:3], vcc, exec
	s_cselect_b32 s3, 0, s36
	s_cselect_b32 s2, s38, s37
	s_not_b32 s3, s3
	s_add_i32 s94, s3, s29
	s_and_b64 s[72:73], vcc, exec
	s_cselect_b32 s3, s9, s17
	s_cselect_b32 s69, s8, s16
	s_lshl_b64 s[72:73], s[94:95], 7
	s_add_u32 s69, s69, s72
	s_addc_u32 s74, s3, s73
	s_mov_b32 s3, s95
	s_lshl_b64 s[72:73], s[2:3], 8
	s_add_u32 s72, s69, s72
	v_cndmask_b32_e32 v2, v138, v0, vcc
	s_addc_u32 s73, s74, s73
	s_add_i32 m0, s42, 0xc000
	s_lshl_b64 s[2:3], s[2:3], 7
	v_lshlrev_b64 v[212:213], 1, v[2:3]
	s_add_u32 s2, s72, s2
	v_lshl_add_u64 v[214:215], s[72:73], 0, v[212:213]
	s_addc_u32 s3, s73, s3
	ds_read_b128 v[180:183], v144
	ds_read_b128 v[188:191], v145
	ds_read_b128 v[196:199], v159
	ds_read_b128 v[204:207], v160
	global_load_lds_dwordx4 v[214:215], off
	v_lshl_add_u64 v[212:213], s[2:3], 0, v[212:213]
	s_add_i32 m0, s42, 0xe000
	s_nop 0
	global_load_lds_dwordx4 v[212:213], off
	s_waitcnt lgkmcnt(4)
	s_barrier
	s_waitcnt lgkmcnt(0)
	v_mfma_f32_16x16x32_bf16 v[128:131], v[164:167], v[180:183], v[128:131]
	ds_read_b128 v[184:187], v144 offset:1024
	v_mfma_f32_16x16x32_bf16 v[124:127], v[172:175], v[180:183], v[124:127]
	ds_read_b128 v[192:195], v145 offset:1024
	v_mfma_f32_16x16x32_bf16 v[120:123], v[164:167], v[188:191], v[120:123]
	ds_read_b128 v[200:203], v159 offset:1024
	v_mfma_f32_16x16x32_bf16 v[116:119], v[172:175], v[188:191], v[116:119]
	ds_read_b128 v[208:211], v160 offset:1024
	v_mfma_f32_16x16x32_bf16 v[104:107], v[164:167], v[196:199], v[104:107]
	v_mfma_f32_16x16x32_bf16 v[100:103], v[172:175], v[196:199], v[100:103]
	v_mfma_f32_16x16x32_bf16 v[88:91], v[164:167], v[204:207], v[88:91]
	v_mfma_f32_16x16x32_bf16 v[84:87], v[172:175], v[204:207], v[84:87]
	s_waitcnt lgkmcnt(0)
	v_mfma_f32_16x16x32_bf16 v[128:131], v[168:171], v[184:187], v[128:131]
	v_mfma_f32_16x16x32_bf16 v[124:127], v[176:179], v[184:187], v[124:127]
	v_mfma_f32_16x16x32_bf16 v[120:123], v[168:171], v[192:195], v[120:123]
	v_mfma_f32_16x16x32_bf16 v[116:119], v[176:179], v[192:195], v[116:119]
	v_mfma_f32_16x16x32_bf16 v[104:107], v[168:171], v[200:203], v[104:107]
	v_mfma_f32_16x16x32_bf16 v[100:103], v[176:179], v[200:203], v[100:103]
	v_mfma_f32_16x16x32_bf16 v[88:91], v[168:171], v[208:211], v[88:91]
	v_mfma_f32_16x16x32_bf16 v[84:87], v[176:179], v[208:211], v[84:87]
	s_barrier
	s_add_u32 s2, s70, s0
	s_mov_b32 m0, s43
	v_lshl_add_u64 v[228:229], s[70:71], 0, v[136:137]
	s_addc_u32 s3, s71, s1
	ds_read_b128 v[212:215], v161
	ds_read_b128 v[220:223], v161 offset:2048
	global_load_lds_dwordx4 v[228:229], off
	v_lshl_add_u64 v[230:231], s[2:3], 0, v[136:137]
	s_mov_b32 m0, s44
	s_nop 0
	global_load_lds_dwordx4 v[230:231], off
	s_barrier
	s_waitcnt lgkmcnt(0)
	v_mfma_f32_16x16x32_bf16 v[112:115], v[212:215], v[180:183], v[112:115]
	ds_read_b128 v[216:219], v161 offset:1024
	ds_read_b128 v[224:227], v161 offset:3072
	v_mfma_f32_16x16x32_bf16 v[108:111], v[220:223], v[180:183], v[108:111]
	s_cmp_lt_u32 s68, s36
	s_cselect_b64 vcc, -1, 0
	v_mfma_f32_16x16x32_bf16 v[96:99], v[212:215], v[188:191], v[96:99]
	s_and_b64 s[70:71], vcc, exec
	s_cselect_b32 s70, s38, s37
	v_mfma_f32_16x16x32_bf16 v[92:95], v[220:223], v[188:191], v[92:95]
	s_sub_i32 s69, s68, s36
	s_min_u32 s94, s68, s69
	v_mfma_f32_16x16x32_bf16 v[80:83], v[212:215], v[196:199], v[80:83]
	s_and_b64 s[72:73], vcc, exec
	s_cselect_b32 s69, s64, s66
	v_mfma_f32_16x16x32_bf16 v[76:79], v[220:223], v[196:199], v[76:79]
	s_cselect_b32 s71, s52, s65
	s_lshl_b64 s[72:73], s[94:95], 7
	v_mfma_f32_16x16x32_bf16 v[72:75], v[212:215], v[204:207], v[72:75]
	v_cndmask_b32_e32 v2, v138, v0, vcc
	s_add_u32 s72, s71, s72
	v_mfma_f32_16x16x32_bf16 v[68:71], v[220:223], v[204:207], v[68:71]
	s_mov_b32 s71, s95
	s_waitcnt lgkmcnt(0)
	v_mfma_f32_16x16x32_bf16 v[112:115], v[216:219], v[184:187], v[112:115]
	s_addc_u32 s73, s69, s73
	v_mfma_f32_16x16x32_bf16 v[108:111], v[224:227], v[184:187], v[108:111]
	v_lshlrev_b64 v[232:233], 1, v[2:3]
	v_mfma_f32_16x16x32_bf16 v[96:99], v[216:219], v[192:195], v[96:99]
	s_lshl_b64 s[70:71], s[70:71], 7
	v_mfma_f32_16x16x32_bf16 v[92:95], v[224:227], v[192:195], v[92:95]
	v_lshl_add_u64 v[234:235], s[72:73], 0, v[232:233]
	v_mfma_f32_16x16x32_bf16 v[80:83], v[216:219], v[200:203], v[80:83]
	s_add_u32 s72, s72, s70
	v_mfma_f32_16x16x32_bf16 v[76:79], v[224:227], v[200:203], v[76:79]
	s_mov_b32 m0, s42
	v_mfma_f32_16x16x32_bf16 v[72:75], v[216:219], v[208:211], v[72:75]
	s_addc_u32 s73, s73, s71
	v_mfma_f32_16x16x32_bf16 v[68:71], v[224:227], v[208:211], v[68:71]
	s_barrier
	ds_read_b128 v[180:183], v144 offset:16384
	ds_read_b128 v[188:191], v145 offset:16384
	ds_read_b128 v[196:199], v159 offset:16384
	ds_read_b128 v[204:207], v160 offset:16384
	global_load_lds_dwordx4 v[234:235], off
	v_lshl_add_u64 v[234:235], s[72:73], 0, v[232:233]
	s_mov_b32 m0, s39
	s_nop 0
	global_load_lds_dwordx4 v[234:235], off
	s_barrier
; #define LDA(dst, b, h) for (int m = 0; m < 4; ++m) for (int k = 0; k < 2; ++k) \
;     dst[m][k] = *reinterpret_cast<const bf16x8*>(SA(b, h) + lds_byte(wr * 64 + m * 16 + fr, k * 32 + fq * 8))
; #define LDB(dst, b, h) for (int n = 0; n < 2; ++n) for (int k = 0; k < 2; ++k) \
;     dst[n][k] = *reinterpret_cast<const bf16x8*>(SB(b, h) + lds_byte(wc * 32 + n * 16 + fr, k * 32 + fq * 8))
; #define MMA(ai, bj, At_, Bt_) do { __builtin_amdgcn_s_setprio(1); \
;     for (int m = 0; m < 4; ++m) for (int n = 0; n < 2; ++n) for (int k = 0; k < 2; ++k) \
;       acc[ai][bj][m][n] = __builtin_amdgcn_mfma_f32_16x16x32_bf16(Bt_[n][k], At_[m][k], acc[ai][bj][m][n], 0, 0, 0); \
;     __builtin_amdgcn_s_setprio(0); } while (0)
; #define WAIT_V(n) asm volatile("s_waitcnt vmcnt(" #n ")" ::: "memory")
; #define WAIT_L(n) asm volatile("s_waitcnt lgkmcnt(" #n ")" ::: "memory")
; #define BAR __builtin_amdgcn_s_barrier()
; #define SCHED __builtin_amdgcn_sched_barrier(0)
; #define STG(P, PTR, LD, O0) do { const bf16_t* _g = (PTR); \
;     __builtin_amdgcn_global_load_lds((const unsigned*)(_g + O0), (lds_u32*)((P) + swave * 1024), 16, 0, 0); \
;     __builtin_amdgcn_global_load_lds((const unsigned*)(_g + (size_t)64 * (LD) + O0), (lds_u32*)((P) + swave * 1024 + 8192), 16, 0, 0); } while (0)
; #define LDA(dst, b, h) for (int m = 0; m < 4; ++m) for (int k = 0; k < 2; ++k) \
;     dst[m][k] = *reinterpret_cast<const bf16x8*>(SA(b, h) + lds_byte(wr * 64 + m * 16 + fr, k * 32 + fq * 8))
; #define LDB(dst, b, h) for (int n = 0; n < 2; ++n) for (int k = 0; k < 2; ++k) \
;     dst[n][k] = *reinterpret_cast<const bf16x8*>(SB(b, h) + lds_byte(wc * 32 + n * 16 + fr, k * 32 + fq * 8))
; #define WAIT_V(n) asm volatile("s_waitcnt vmcnt(" #n ")" ::: "memory")
; __device__ __forceinline__ void gemm_stream(int swave, const GemmJob& J, char* shm, int vb, int G) {
;     ...
;       LDA(At, 0, 1); STGA(SA(0, 0), xA, xA1, k2, 0);
;       BAR; WAIT_L(0); MMA(1, 0, At, B0); BAR; SCHED;
;       STG(SB(0, 1), b2 + hB, ldb, offB0);
;       WAIT_V(6); BAR; MMA(1, 1, At, B1); BAR;
;       LDB(B0, 1, 0); SCHED; LDA(At, 1, 0); STGA(SA(0, 1), xA, xA1, k2, 1);
;       WAIT_L(8); BAR; WAIT_L(0); MMA(0, 0, At, B0); BAR; SCHED;
;       LDB(B1, 1, 1); STG(SB(1, 0), b3, ldb, offB0);
;       BAR; WAIT_L(0); MMA(0, 1, At, B1); BAR;
;       LDA(At, 1, 1); STGA(SA(1, 0), xA, xA1, k2 + 1, 0);
	s_waitcnt lgkmcnt(0)
	v_mfma_f32_16x16x32_bf16 v[64:67], v[164:167], v[180:183], v[64:67]
	ds_read_b128 v[184:187], v144 offset:17408
	v_mfma_f32_16x16x32_bf16 v[60:63], v[172:175], v[180:183], v[60:63]
	ds_read_b128 v[192:195], v145 offset:17408
	v_mfma_f32_16x16x32_bf16 v[56:59], v[164:167], v[188:191], v[56:59]
	ds_read_b128 v[200:203], v159 offset:17408
	v_mfma_f32_16x16x32_bf16 v[52:55], v[172:175], v[188:191], v[52:55]
	ds_read_b128 v[208:211], v160 offset:17408
	v_mfma_f32_16x16x32_bf16 v[40:43], v[164:167], v[196:199], v[40:43]
	v_mfma_f32_16x16x32_bf16 v[36:39], v[172:175], v[196:199], v[36:39]
	v_mfma_f32_16x16x32_bf16 v[24:27], v[164:167], v[204:207], v[24:27]
	v_mfma_f32_16x16x32_bf16 v[20:23], v[172:175], v[204:207], v[20:23]
	s_waitcnt lgkmcnt(0)
	v_mfma_f32_16x16x32_bf16 v[64:67], v[168:171], v[184:187], v[64:67]
	v_mfma_f32_16x16x32_bf16 v[60:63], v[176:179], v[184:187], v[60:63]
	v_mfma_f32_16x16x32_bf16 v[56:59], v[168:171], v[192:195], v[56:59]
	v_mfma_f32_16x16x32_bf16 v[52:55], v[176:179], v[192:195], v[52:55]
	v_mfma_f32_16x16x32_bf16 v[40:43], v[168:171], v[200:203], v[40:43]
	v_mfma_f32_16x16x32_bf16 v[36:39], v[176:179], v[200:203], v[36:39]
	v_mfma_f32_16x16x32_bf16 v[24:27], v[168:171], v[208:211], v[24:27]
	v_mfma_f32_16x16x32_bf16 v[20:23], v[176:179], v[208:211], v[20:23]
	s_barrier
	s_add_u32 s2, s2, s0
	s_addc_u32 s3, s3, s1
	v_lshl_add_u64 v[234:235], s[2:3], 0, v[136:137]
	s_add_u32 s2, s2, s0
	s_mov_b32 m0, s45
	s_addc_u32 s3, s3, s1
	global_load_lds_dwordx4 v[234:235], off
	v_lshl_add_u64 v[236:237], s[2:3], 0, v[136:137]
	s_mov_b32 m0, s46
	s_nop 0
	global_load_lds_dwordx4 v[236:237], off
	s_waitcnt vmcnt(6)
	s_barrier
	v_mfma_f32_16x16x32_bf16 v[48:51], v[212:215], v[180:183], v[48:51]
	v_mfma_f32_16x16x32_bf16 v[44:47], v[220:223], v[180:183], v[44:47]
	v_mfma_f32_16x16x32_bf16 v[32:35], v[212:215], v[188:191], v[32:35]
	v_mfma_f32_16x16x32_bf16 v[28:31], v[220:223], v[188:191], v[28:31]
	v_mfma_f32_16x16x32_bf16 v[16:19], v[212:215], v[196:199], v[16:19]
	v_mfma_f32_16x16x32_bf16 v[12:15], v[220:223], v[196:199], v[12:15]
	v_mfma_f32_16x16x32_bf16 v[8:11], v[212:215], v[204:207], v[8:11]
	v_mfma_f32_16x16x32_bf16 v[4:7], v[220:223], v[204:207], v[4:7]
	v_mfma_f32_16x16x32_bf16 v[48:51], v[216:219], v[184:187], v[48:51]
	v_mfma_f32_16x16x32_bf16 v[44:47], v[224:227], v[184:187], v[44:47]
	v_mfma_f32_16x16x32_bf16 v[32:35], v[216:219], v[192:195], v[32:35]
	v_mfma_f32_16x16x32_bf16 v[28:31], v[224:227], v[192:195], v[28:31]
	v_mfma_f32_16x16x32_bf16 v[16:19], v[216:219], v[200:203], v[16:19]
	v_mfma_f32_16x16x32_bf16 v[12:15], v[224:227], v[200:203], v[12:15]
	v_mfma_f32_16x16x32_bf16 v[8:11], v[216:219], v[208:211], v[8:11]
	v_mfma_f32_16x16x32_bf16 v[4:7], v[224:227], v[208:211], v[4:7]
	s_barrier
	ds_read_b128 v[164:167], v162
	ds_read_b128 v[168:171], v162 offset:1024
	ds_read_b128 v[172:175], v162 offset:2048
	ds_read_b128 v[176:179], v162 offset:3072
	s_add_u32 s2, s72, s70
	s_addc_u32 s3, s73, s71
	v_lshl_add_u64 v[212:213], s[2:3], 0, v[232:233]
	s_add_u32 s2, s2, s70
	s_mov_b32 m0, s47
	s_addc_u32 s3, s3, s71
	ds_read_b128 v[180:183], v144 offset:32768
	ds_read_b128 v[188:191], v145 offset:32768
	ds_read_b128 v[196:199], v159 offset:32768
	ds_read_b128 v[204:207], v160 offset:32768
	global_load_lds_dwordx4 v[212:213], off
	v_lshl_add_u64 v[212:213], s[2:3], 0, v[232:233]
	s_mov_b32 m0, s48
	s_nop 0
	global_load_lds_dwordx4 v[212:213], off
	s_waitcnt lgkmcnt(4)
	s_barrier
	s_waitcnt lgkmcnt(0)
	v_mfma_f32_16x16x32_bf16 v[128:131], v[164:167], v[180:183], v[128:131]
	ds_read_b128 v[184:187], v144 offset:33792
	v_mfma_f32_16x16x32_bf16 v[124:127], v[172:175], v[180:183], v[124:127]
	ds_read_b128 v[192:195], v145 offset:33792
	v_mfma_f32_16x16x32_bf16 v[120:123], v[164:167], v[188:191], v[120:123]
	ds_read_b128 v[200:203], v159 offset:33792
	v_mfma_f32_16x16x32_bf16 v[116:119], v[172:175], v[188:191], v[116:119]
	ds_read_b128 v[208:211], v160 offset:33792
	v_mfma_f32_16x16x32_bf16 v[104:107], v[164:167], v[196:199], v[104:107]
	v_mfma_f32_16x16x32_bf16 v[100:103], v[172:175], v[196:199], v[100:103]
	v_mfma_f32_16x16x32_bf16 v[88:91], v[164:167], v[204:207], v[88:91]
	v_mfma_f32_16x16x32_bf16 v[84:87], v[172:175], v[204:207], v[84:87]
	s_waitcnt lgkmcnt(0)
	v_mfma_f32_16x16x32_bf16 v[128:131], v[168:171], v[184:187], v[128:131]
	v_mfma_f32_16x16x32_bf16 v[124:127], v[176:179], v[184:187], v[124:127]
	v_mfma_f32_16x16x32_bf16 v[120:123], v[168:171], v[192:195], v[120:123]
	v_mfma_f32_16x16x32_bf16 v[116:119], v[176:179], v[192:195], v[116:119]
	v_mfma_f32_16x16x32_bf16 v[104:107], v[168:171], v[200:203], v[104:107]
	v_mfma_f32_16x16x32_bf16 v[100:103], v[176:179], v[200:203], v[100:103]
	v_mfma_f32_16x16x32_bf16 v[88:91], v[168:171], v[208:211], v[88:91]
	v_mfma_f32_16x16x32_bf16 v[84:87], v[176:179], v[208:211], v[84:87]
	s_barrier
	v_lshl_add_u64 v[228:229], v[228:229], 0, s[22:23]
	s_add_i32 m0, s42, 0x18000
	ds_read_b128 v[212:215], v163
	ds_read_b128 v[220:223], v163 offset:2048
	global_load_lds_dwordx4 v[228:229], off
	v_lshl_add_u64 v[228:229], v[230:231], 0, s[22:23]
	s_add_i32 m0, s42, 0x1a000
	s_nop 0
	global_load_lds_dwordx4 v[228:229], off
	s_barrier
; #define LDA(dst, b, h) for (int m = 0; m < 4; ++m) for (int k = 0; k < 2; ++k) \
;     dst[m][k] = *reinterpret_cast<const bf16x8*>(SA(b, h) + lds_byte(wr * 64 + m * 16 + fr, k * 32 + fq * 8))
; #define MMA(ai, bj, At_, Bt_) do { __builtin_amdgcn_s_setprio(1); \
;     for (int m = 0; m < 4; ++m) for (int n = 0; n < 2; ++n) for (int k = 0; k < 2; ++k) \
;       acc[ai][bj][m][n] = __builtin_amdgcn_mfma_f32_16x16x32_bf16(Bt_[n][k], At_[m][k], acc[ai][bj][m][n], 0, 0, 0); \
;     __builtin_amdgcn_s_setprio(0); } while (0)
; #define WAIT_V(n) asm volatile("s_waitcnt vmcnt(" #n ")" ::: "memory")
; #define WAIT_L(n) asm volatile("s_waitcnt lgkmcnt(" #n ")" ::: "memory")
; #define BAR __builtin_amdgcn_s_barrier()
; #define SCHED __builtin_amdgcn_sched_barrier(0)
; #define STG(P, PTR, LD, O0) do { const bf16_t* _g = (PTR); \
;     __builtin_amdgcn_global_load_lds((const unsigned*)(_g + O0), (lds_u32*)((P) + swave * 1024), 16, 0, 0); \
;     __builtin_amdgcn_global_load_lds((const unsigned*)(_g + (size_t)64 * (LD) + O0), (lds_u32*)((P) + swave * 1024 + 8192), 16, 0, 0); } while (0)
; #define LDA(dst, b, h) for (int m = 0; m < 4; ++m) for (int k = 0; k < 2; ++k) \
;     dst[m][k] = *reinterpret_cast<const bf16x8*>(SA(b, h) + lds_byte(wr * 64 + m * 16 + fr, k * 32 + fq * 8))
; #define MMA(ai, bj, At_, Bt_) do { __builtin_amdgcn_s_setprio(1); \
;     for (int m = 0; m < 4; ++m) for (int n = 0; n < 2; ++n) for (int k = 0; k < 2; ++k) \
;       acc[ai][bj][m][n] = __builtin_amdgcn_mfma_f32_16x16x32_bf16(Bt_[n][k], At_[m][k], acc[ai][bj][m][n], 0, 0, 0); \
;     __builtin_amdgcn_s_setprio(0); } while (0)
; #define WAIT_V(n) asm volatile("s_waitcnt vmcnt(" #n ")" ::: "memory")
; #define WAIT_L(n) asm volatile("s_waitcnt lgkmcnt(" #n ")" ::: "memory")
; #define BAR __builtin_amdgcn_s_barrier()
; #define SCHED __builtin_amdgcn_sched_barrier(0)
; __device__ __forceinline__ void gemm_stream(int swave, const GemmJob& J, char* shm, int vb, int G) {
;     ...
;       BAR; WAIT_L(0); MMA(0, 1, At, B1); BAR;
;       LDA(At, 1, 1); STGA(SA(1, 0), xA, xA1, k2 + 1, 0);
;       BAR; WAIT_L(0); MMA(1, 0, At, B0); BAR; SCHED;
;       STG(SB(1, 1), b3 + hB, ldb, offB0);
;       WAIT_V(6); BAR; MMA(1, 1, At, B1); BAR;
;     }
	s_waitcnt lgkmcnt(0)
	v_mfma_f32_16x16x32_bf16 v[112:115], v[212:215], v[180:183], v[112:115]
	ds_read_b128 v[216:219], v163 offset:1024
	ds_read_b128 v[224:227], v163 offset:3072
	v_mfma_f32_16x16x32_bf16 v[108:111], v[220:223], v[180:183], v[108:111]
	s_or_b32 s68, s68, 1
	s_cmp_lt_u32 s68, s36
	v_mfma_f32_16x16x32_bf16 v[96:99], v[212:215], v[188:191], v[96:99]
	s_cselect_b64 vcc, -1, 0
	s_and_b64 s[2:3], vcc, exec
	v_mfma_f32_16x16x32_bf16 v[92:95], v[220:223], v[188:191], v[92:95]
	s_cselect_b32 s69, s38, s37
	s_sub_i32 s2, s68, s36
	v_mfma_f32_16x16x32_bf16 v[80:83], v[212:215], v[196:199], v[80:83]
	s_min_u32 s94, s68, s2
	s_and_b64 s[2:3], vcc, exec
	v_mfma_f32_16x16x32_bf16 v[76:79], v[220:223], v[196:199], v[76:79]
	s_cselect_b32 s64, s64, s66
	s_cselect_b32 s52, s52, s65
	v_mfma_f32_16x16x32_bf16 v[72:75], v[212:215], v[204:207], v[72:75]
	s_lshl_b64 s[2:3], s[94:95], 7
	v_cndmask_b32_e32 v2, v138, v0, vcc
	v_mfma_f32_16x16x32_bf16 v[68:71], v[220:223], v[204:207], v[68:71]
	s_add_u32 s2, s52, s2
	s_waitcnt lgkmcnt(0)
	v_mfma_f32_16x16x32_bf16 v[112:115], v[216:219], v[184:187], v[112:115]
	s_addc_u32 s3, s64, s3
	v_mfma_f32_16x16x32_bf16 v[108:111], v[224:227], v[184:187], v[108:111]
	v_lshlrev_b64 v[228:229], 1, v[2:3]
	v_mfma_f32_16x16x32_bf16 v[96:99], v[216:219], v[192:195], v[96:99]
	s_lshl_b32 s52, s69, 7
	v_mfma_f32_16x16x32_bf16 v[92:95], v[224:227], v[192:195], v[92:95]
	v_lshl_add_u64 v[230:231], s[2:3], 0, v[228:229]
	v_mfma_f32_16x16x32_bf16 v[80:83], v[216:219], v[200:203], v[80:83]
	s_add_u32 s2, s2, s52
	v_mfma_f32_16x16x32_bf16 v[76:79], v[224:227], v[200:203], v[76:79]
	s_mov_b32 m0, s54
	v_mfma_f32_16x16x32_bf16 v[72:75], v[216:219], v[208:211], v[72:75]
	s_addc_u32 s3, s3, 0
	v_mfma_f32_16x16x32_bf16 v[68:71], v[224:227], v[208:211], v[68:71]
	s_barrier
	ds_read_b128 v[180:183], v144 offset:49152
	ds_read_b128 v[188:191], v145 offset:49152
	ds_read_b128 v[196:199], v159 offset:49152
	ds_read_b128 v[204:207], v160 offset:49152
	global_load_lds_dwordx4 v[230:231], off
	v_lshl_add_u64 v[228:229], s[2:3], 0, v[228:229]
	s_mov_b32 m0, s55
	s_nop 0
	global_load_lds_dwordx4 v[228:229], off
	s_barrier
	s_waitcnt lgkmcnt(0)
	v_mfma_f32_16x16x32_bf16 v[64:67], v[164:167], v[180:183], v[64:67]
	ds_read_b128 v[184:187], v144 offset:50176
	v_mfma_f32_16x16x32_bf16 v[60:63], v[172:175], v[180:183], v[60:63]
	ds_read_b128 v[192:195], v145 offset:50176
	v_mfma_f32_16x16x32_bf16 v[56:59], v[164:167], v[188:191], v[56:59]
	ds_read_b128 v[200:203], v159 offset:50176
	v_mfma_f32_16x16x32_bf16 v[52:55], v[172:175], v[188:191], v[52:55]
	ds_read_b128 v[208:211], v160 offset:50176
	v_mfma_f32_16x16x32_bf16 v[40:43], v[164:167], v[196:199], v[40:43]
	v_mfma_f32_16x16x32_bf16 v[36:39], v[172:175], v[196:199], v[36:39]
	v_mfma_f32_16x16x32_bf16 v[24:27], v[164:167], v[204:207], v[24:27]
	v_mfma_f32_16x16x32_bf16 v[20:23], v[172:175], v[204:207], v[20:23]
	s_waitcnt lgkmcnt(0)
	v_mfma_f32_16x16x32_bf16 v[64:67], v[168:171], v[184:187], v[64:67]
	v_mfma_f32_16x16x32_bf16 v[60:63], v[176:179], v[184:187], v[60:63]
	v_mfma_f32_16x16x32_bf16 v[56:59], v[168:171], v[192:195], v[56:59]
	v_mfma_f32_16x16x32_bf16 v[52:55], v[176:179], v[192:195], v[52:55]
	v_mfma_f32_16x16x32_bf16 v[40:43], v[168:171], v[200:203], v[40:43]
	v_mfma_f32_16x16x32_bf16 v[36:39], v[176:179], v[200:203], v[36:39]
	v_mfma_f32_16x16x32_bf16 v[24:27], v[168:171], v[208:211], v[24:27]
	v_mfma_f32_16x16x32_bf16 v[20:23], v[176:179], v[208:211], v[20:23]
	s_barrier
	v_lshl_add_u64 v[164:165], v[234:235], 0, s[22:23]
	s_add_i32 m0, s42, 0x1c000
	s_nop 0
	global_load_lds_dwordx4 v[164:165], off
	v_lshl_add_u64 v[164:165], v[236:237], 0, s[22:23]
	s_add_i32 m0, s42, 0x1e000
	s_nop 0
	global_load_lds_dwordx4 v[164:165], off
	s_waitcnt vmcnt(6)
	s_barrier
	v_mfma_f32_16x16x32_bf16 v[48:51], v[212:215], v[180:183], v[48:51]
	v_mfma_f32_16x16x32_bf16 v[44:47], v[220:223], v[180:183], v[44:47]
	s_add_i32 s29, s29, 2
	v_mfma_f32_16x16x32_bf16 v[32:35], v[212:215], v[188:191], v[32:35]
	s_add_u32 s20, s20, 0x100
	v_mfma_f32_16x16x32_bf16 v[28:31], v[220:223], v[188:191], v[28:31]
	s_addc_u32 s21, s21, 0
	v_mfma_f32_16x16x32_bf16 v[16:19], v[212:215], v[196:199], v[16:19]
	s_cmp_ge_u32 s33, s49
	v_mfma_f32_16x16x32_bf16 v[12:15], v[220:223], v[196:199], v[12:15]
	s_mov_b32 s2, s33
	v_mfma_f32_16x16x32_bf16 v[8:11], v[212:215], v[204:207], v[8:11]
	v_mfma_f32_16x16x32_bf16 v[4:7], v[220:223], v[204:207], v[4:7]
	v_mfma_f32_16x16x32_bf16 v[48:51], v[216:219], v[184:187], v[48:51]
	v_mfma_f32_16x16x32_bf16 v[44:47], v[224:227], v[184:187], v[44:47]
	v_mfma_f32_16x16x32_bf16 v[32:35], v[216:219], v[192:195], v[32:35]
	v_mfma_f32_16x16x32_bf16 v[28:31], v[224:227], v[192:195], v[28:31]
	v_mfma_f32_16x16x32_bf16 v[16:19], v[216:219], v[200:203], v[16:19]
	v_mfma_f32_16x16x32_bf16 v[12:15], v[224:227], v[200:203], v[12:15]
	v_mfma_f32_16x16x32_bf16 v[8:11], v[216:219], v[208:211], v[8:11]
	v_mfma_f32_16x16x32_bf16 v[4:7], v[224:227], v[208:211], v[4:7]
	s_barrier
; __device__ __forceinline__ unsigned pk2(float lo, float hi) { f32x2_t v = {lo, hi}; bf16x2_t b = __builtin_convertvector(v, bf16x2_t); return __builtin_bit_cast(unsigned, b); }
; #define WAIT_V(n) asm volatile("s_waitcnt vmcnt(" #n ")" ::: "memory")
; #define BAR __builtin_amdgcn_s_barrier()
; #define WAIT_V(n) asm volatile("s_waitcnt vmcnt(" #n ")" ::: "memory")
; #define BAR __builtin_amdgcn_s_barrier()
; __device__ __forceinline__ void gemm_stream(int swave, const GemmJob& J, char* shm, int vb, int G) {
;     ...
;     {
;       bf16_t* C = (bf16_t*)((char*)J.c0 + (size_t)cg * J.strideC);
; #pragma unroll
;       for (int ai = 0; ai < 2; ++ai)
; #pragma unroll
;         for (int m = 0; m < 4; ++m)
; #pragma unroll
;           for (int bj = 0; bj < 2; ++bj) {
;             const f32x4 v0 = acc[ai][bj][m][0], v1 = acc[ai][bj][m][1];
;             uint4 o; o.x = pk2(v0[0], v0[1]); o.y = pk2(v0[2], v0[3]); o.z = pk2(v1[0], v1[1]); o.w = pk2(v1[2], v1[3]);
;             *(uint4*)(C + (size_t)(cbrow + ai * 128 + wr * 64 + m * 16 + fr) * J.ldc + cbcol + bj * 128 + wc * 32 + fq * 8) = o;
;           }
;     }
;     if (!has_next) break;
; #pragma unroll
;     for (int a_ = 0; a_ < 2; ++a_)
; #pragma unroll
;       for (int b_ = 0; b_ < 2; ++b_)
; #pragma unroll
;         for (int m = 0; m < 4; ++m)
; #pragma unroll
;           for (int n = 0; n < 2; ++n) acc[a_][b_][m][n] = (f32x4){0.f, 0.f, 0.f, 0.f};
;     id = nid; cg = ng; cbrow = nbrow; cbcol = nbcol; cA = nA; cA1 = nA1; cB = nB;
;   }
;   WAIT_V(0);
;   if (wr == 0) BAR;
;   BAR;
	s_cbranch_scc0 .LBB0_729
	v_add_u32_e32 v164, s5, v1
	s_ashr_i32 s5, s4, 31
	s_lshl_b64 s[2:3], s[4:5], 1
	v_ashrrev_i32_e32 v2, 31, v164
	s_add_u32 s2, s50, s2
	v_cvt_pk_bf16_f32 v128, v128, v129
	v_cvt_pk_bf16_f32 v129, v130, v131
	v_cvt_pk_bf16_f32 v130, v124, v125
	v_mul_lo_u32 v2, v2, s18
	v_mad_u64_u32 v[124:125], s[4:5], v164, s18, 0
	s_addc_u32 s3, s51, s3
	v_add_u32_e32 v125, v125, v2
	v_lshl_add_u64 v[124:125], v[124:125], 1, s[2:3]
	v_mov_b32_e32 v141, v3
	v_lshl_add_u64 v[124:125], v[124:125], 0, v[140:141]
	v_mov_b32_e32 v143, v3
	v_lshl_add_u64 v[124:125], v[124:125], 0, v[142:143]
	s_lshl_b32 s2, s18, 5
	s_mov_b32 s3, 0
	s_mul_i32 s4, s18, 0xa0
	s_mov_b32 s5, 0
	v_cvt_pk_bf16_f32 v112, v112, v113
	v_cvt_pk_bf16_f32 v113, v114, v115
	v_cvt_pk_bf16_f32 v114, v108, v109
	v_cvt_pk_bf16_f32 v115, v110, v111
	global_store_dwordx4 v[124:125], v[112:115], off offset:256
	v_cvt_pk_bf16_f32 v131, v126, v127
	v_cvt_pk_bf16_f32 v96, v96, v97
	v_lshl_add_u64 v[112:113], v[124:125], 0, s[2:3]
	v_cvt_pk_bf16_f32 v97, v98, v99
	v_cvt_pk_bf16_f32 v98, v92, v93
	v_cvt_pk_bf16_f32 v99, v94, v95
	global_store_dwordx4 v[124:125], v[128:131], off
	global_store_dwordx4 v[112:113], v[96:99], off offset:256
	v_cvt_pk_bf16_f32 v108, v120, v121
	v_cvt_pk_bf16_f32 v109, v122, v123
	v_lshl_add_u64 v[96:97], v[112:113], 0, s[2:3]
	v_cvt_pk_bf16_f32 v110, v116, v117
	v_cvt_pk_bf16_f32 v111, v118, v119
	v_cvt_pk_bf16_f32 v80, v80, v81
	v_cvt_pk_bf16_f32 v81, v82, v83
	v_cvt_pk_bf16_f32 v82, v76, v77
	v_cvt_pk_bf16_f32 v83, v78, v79
	global_store_dwordx4 v[112:113], v[108:111], off
	global_store_dwordx4 v[96:97], v[80:83], off offset:256
	v_cvt_pk_bf16_f32 v64, v64, v65
	v_cvt_pk_bf16_f32 v65, v66, v67
	v_lshl_add_u64 v[80:81], v[96:97], 0, s[2:3]
	v_cvt_pk_bf16_f32 v66, v60, v61
	v_lshl_add_u64 v[60:61], v[80:81], 0, s[4:5]
	v_cvt_pk_bf16_f32 v72, v72, v73
	v_cvt_pk_bf16_f32 v73, v74, v75
	v_cvt_pk_bf16_f32 v74, v68, v69
	v_cvt_pk_bf16_f32 v67, v62, v63
	v_cvt_pk_bf16_f32 v92, v104, v105
	v_cvt_pk_bf16_f32 v93, v106, v107
	v_cvt_pk_bf16_f32 v94, v100, v101
	v_cvt_pk_bf16_f32 v95, v102, v103
	v_cvt_pk_bf16_f32 v76, v88, v89
	v_cvt_pk_bf16_f32 v77, v90, v91
	v_cvt_pk_bf16_f32 v78, v84, v85
	v_cvt_pk_bf16_f32 v79, v86, v87
	v_cvt_pk_bf16_f32 v75, v70, v71
	v_cvt_pk_bf16_f32 v48, v48, v49
	v_cvt_pk_bf16_f32 v49, v50, v51
	v_cvt_pk_bf16_f32 v50, v44, v45
	v_cvt_pk_bf16_f32 v51, v46, v47
	global_store_dwordx4 v[96:97], v[92:95], off
	global_store_dwordx4 v[80:81], v[76:79], off
	global_store_dwordx4 v[80:81], v[72:75], off offset:256
	global_store_dwordx4 v[60:61], v[48:51], off offset:256
	v_cvt_pk_bf16_f32 v32, v32, v33
	v_cvt_pk_bf16_f32 v33, v34, v35
	v_lshl_add_u64 v[48:49], v[60:61], 0, s[2:3]
	v_cvt_pk_bf16_f32 v34, v28, v29
	v_cvt_pk_bf16_f32 v35, v30, v31
	global_store_dwordx4 v[60:61], v[64:67], off
	global_store_dwordx4 v[48:49], v[32:35], off offset:256
	v_cvt_pk_bf16_f32 v44, v56, v57
	v_cvt_pk_bf16_f32 v45, v58, v59
	v_lshl_add_u64 v[32:33], v[48:49], 0, s[2:3]
	v_cvt_pk_bf16_f32 v46, v52, v53
	v_cvt_pk_bf16_f32 v47, v54, v55
	v_cvt_pk_bf16_f32 v16, v16, v17
	v_cvt_pk_bf16_f32 v17, v18, v19
	v_cvt_pk_bf16_f32 v18, v12, v13
	v_cvt_pk_bf16_f32 v19, v14, v15
	global_store_dwordx4 v[48:49], v[44:47], off
	global_store_dwordx4 v[32:33], v[16:19], off offset:256
	v_cvt_pk_bf16_f32 v28, v40, v41
	v_cvt_pk_bf16_f32 v29, v42, v43
	v_lshl_add_u64 v[16:17], v[32:33], 0, s[2:3]
	v_cvt_pk_bf16_f32 v30, v36, v37
	v_cvt_pk_bf16_f32 v31, v38, v39
	v_cvt_pk_bf16_f32 v12, v24, v25
	v_cvt_pk_bf16_f32 v13, v26, v27
	v_cvt_pk_bf16_f32 v14, v20, v21
	v_cvt_pk_bf16_f32 v15, v22, v23
	v_cvt_pk_bf16_f32 v8, v8, v9
	v_cvt_pk_bf16_f32 v9, v10, v11
	v_cvt_pk_bf16_f32 v10, v4, v5
	v_cvt_pk_bf16_f32 v11, v6, v7
	s_and_b64 vcc, exec, s[6:7]
	s_mov_b64 s[2:3], s[14:15]
	s_mov_b64 s[16:17], s[12:13]
	s_mov_b64 s[8:9], s[10:11]
	s_mov_b32 s4, s56
	s_mov_b32 s5, s28
	global_store_dwordx4 v[32:33], v[28:31], off
	global_store_dwordx4 v[16:17], v[12:15], off
	global_store_dwordx4 v[16:17], v[8:11], off offset:256
	s_cbranch_vccz .LBB0_726
	s_waitcnt vmcnt(0)
	s_movk_i32 s66, 0x100
	v_cmp_gt_u32_e32 vcc, s66, v135
	s_and_saveexec_b64 s[0:1], vcc
	s_cbranch_execz .LBB0_733
	s_barrier
